# P1: first row's x loads issued before the adaLN table build (overlap HBM round trip with table preamble)
# baseline (speedup 1.0000x reference)
; __device__ __forceinline__ void p1_rows(const Params& P, LAS unsigned char* lds, int G) {
;     ...
;     for (int idx = tid; idx < 2 * DM; idx += NTHREADS) { const int b = idx >> 11, col = idx & (DM - 1);
;         float sh = P.b_ada[col], sc = P.b_ada[DM + col];
;         for (int ks = 0; ks < KS_ADA; ++ks) { sh += adap[(size_t)(ks * 2 + b) * NADA + col]; sc += adap[(size_t)(ks * 2 + b) * NADA + DM + col]; }
;         TA[idx] = P.g_pre_mix[col] * (1.0f + sc); TC[idx] = sh; }
;     ...
;     for (int m = blockIdx.x * 8 + wave; m < M; m += G * 8) {
;         const int b = m >> 13; const f32x4* xr = (const f32x4*)(P.x + (size_t)m * DM) + lane;
;         f32x4 v[8]; float ss = 0.f;
; #pragma unroll
;         for (int j = 0; j < 8; ++j) { v[j] = __builtin_nontemporal_load(xr + 64 * j); ss += (v[j][0] * v[j][0] + v[j][1] * v[j][1]) + (v[j][2] * v[j][2] + v[j][3] * v[j][3]); }
.LBB0_156:
	s_or_b64 exec, exec, s[4:5]
	v_mov_b32_e32 v8, v168
	s_and_b32 s6, s2, 7
	s_lshl_b32 s6, s6, 11
	s_lshr_b32 s7, s2, 3
	s_lshl_b32 s7, s7, 3
	s_add_i32 s6, s6, s7
	s_lshl_b32 s7, s2, 3
	s_cmpk_eq_u32 s92, 0x100
	s_cselect_b32 s6, s6, s7
	v_lshrrev_b32_e32 v254, 6, v168
	v_add_u32_e32 v254, s6, v254
	v_mov_b32_e32 v255, 0
	v_and_b32_e32 v130, 63, v168
	v_lshlrev_b64 v[254:255], 13, v[254:255]
	v_lshlrev_b32_e32 v130, 4, v130
	s_mov_b64 s[6:7], 0x1000
	v_or_b32_e32 v254, v254, v130
	v_lshl_add_u64 v[254:255], s[60:61], 0, v[254:255]
	v_lshl_add_u64 v[254:255], v[254:255], 0, s[6:7]
	global_load_dwordx4 v[170:173], v[254:255], off offset:-4096 nt
	global_load_dwordx4 v[202:205], v[254:255], off offset:-3072 nt
	global_load_dwordx4 v[210:213], v[254:255], off offset:-2048 nt
	global_load_dwordx4 v[214:217], v[254:255], off offset:-1024 nt
	global_load_dwordx4 v[218:221], v[254:255], off nt
	global_load_dwordx4 v[222:225], v[254:255], off offset:1024 nt
	global_load_dwordx4 v[246:249], v[254:255], off offset:2048 nt
	global_load_dwordx4 v[250:253], v[254:255], off offset:3072 nt
	s_movk_i32 s4, 0x1000
	s_waitcnt lgkmcnt(0)
	s_barrier
	s_nop 0
	v_cmp_gt_i32_e32 vcc, s4, v8
	s_and_saveexec_b64 s[4:5], vcc
	s_cbranch_execz .LBB0_161
	v_lshlrev_b32_e32 v0, 4, v8
	v_mov_b32_e32 v6, v0
	s_add_u32 s8, s68, 0x2000
	s_addc_u32 s9, s69, 0
	global_load_dwordx4 v[12:15], v0, s[68:69]
	global_load_dwordx4 v[16:19], v0, s[8:9]
	global_load_dwordx4 v[20:23], v0, s[70:71]
	s_add_u32 s8, s58, 0x0
	s_addc_u32 s9, s59, 0
	global_load_dwordx4 v[24:27], v6, s[8:9]
	s_add_u32 s8, s58, 0x2000
	s_addc_u32 s9, s59, 0
	global_load_dwordx4 v[28:31], v6, s[8:9]
	s_add_u32 s8, s58, 0x18000
	s_addc_u32 s9, s59, 0
	global_load_dwordx4 v[32:35], v6, s[8:9]
	s_add_u32 s8, s58, 0x1a000
	s_addc_u32 s9, s59, 0
	global_load_dwordx4 v[36:39], v6, s[8:9]
	s_add_u32 s8, s58, 0x30000
	s_addc_u32 s9, s59, 0
	global_load_dwordx4 v[40:43], v6, s[8:9]
	s_add_u32 s8, s58, 0x32000
	s_addc_u32 s9, s59, 0
	global_load_dwordx4 v[44:47], v6, s[8:9]
	s_add_u32 s8, s58, 0x48000
	s_addc_u32 s9, s59, 0
	global_load_dwordx4 v[48:51], v6, s[8:9]
	s_add_u32 s8, s58, 0x4a000
	s_addc_u32 s9, s59, 0
	global_load_dwordx4 v[52:55], v6, s[8:9]
	s_add_u32 s8, s58, 0x60000
	s_addc_u32 s9, s59, 0
	global_load_dwordx4 v[56:59], v6, s[8:9]
	s_add_u32 s8, s58, 0x62000
	s_addc_u32 s9, s59, 0
	global_load_dwordx4 v[60:63], v6, s[8:9]
	s_add_u32 s8, s58, 0x78000
	s_addc_u32 s9, s59, 0
	global_load_dwordx4 v[64:67], v6, s[8:9]
	s_add_u32 s8, s58, 0x7a000
	s_addc_u32 s9, s59, 0
	global_load_dwordx4 v[68:71], v6, s[8:9]
	s_add_u32 s8, s58, 0x90000
	s_addc_u32 s9, s59, 0
	global_load_dwordx4 v[72:75], v6, s[8:9]
	s_add_u32 s8, s58, 0x92000
	s_addc_u32 s9, s59, 0
	global_load_dwordx4 v[76:79], v6, s[8:9]
	s_add_u32 s8, s58, 0xa8000
	s_addc_u32 s9, s59, 0
	global_load_dwordx4 v[80:83], v6, s[8:9]
	s_add_u32 s8, s58, 0xaa000
	s_addc_u32 s9, s59, 0
	global_load_dwordx4 v[84:87], v6, s[8:9]
	s_add_u32 s8, s58, 0xc0000
	s_addc_u32 s9, s59, 0
	global_load_dwordx4 v[88:91], v6, s[8:9]
	s_add_u32 s8, s58, 0xc2000
	s_addc_u32 s9, s59, 0
	global_load_dwordx4 v[92:95], v6, s[8:9]
	s_add_u32 s8, s58, 0xd8000
	s_addc_u32 s9, s59, 0
	global_load_dwordx4 v[96:99], v6, s[8:9]
	s_add_u32 s8, s58, 0xda000
	s_addc_u32 s9, s59, 0
	global_load_dwordx4 v[100:103], v6, s[8:9]
	s_add_u32 s8, s58, 0xf0000
	s_addc_u32 s9, s59, 0
	global_load_dwordx4 v[104:107], v6, s[8:9]
	s_add_u32 s8, s58, 0xf2000
	s_addc_u32 s9, s59, 0
	global_load_dwordx4 v[108:111], v6, s[8:9]
	s_add_u32 s8, s58, 0x108000
	s_addc_u32 s9, s59, 0
	global_load_dwordx4 v[112:115], v6, s[8:9]
	s_add_u32 s8, s58, 0x10a000
	s_addc_u32 s9, s59, 0
	global_load_dwordx4 v[116:119], v6, s[8:9]
	s_add_u32 s8, s58, 0x120000
	s_addc_u32 s9, s59, 0
	global_load_dwordx4 v[120:123], v6, s[8:9]
	s_add_u32 s8, s58, 0x122000
	s_addc_u32 s9, s59, 0
	global_load_dwordx4 v[132:135], v6, s[8:9]
	s_add_u32 s8, s58, 0x138000
	s_addc_u32 s9, s59, 0
	global_load_dwordx4 v[136:139], v6, s[8:9]
	s_add_u32 s8, s58, 0x13a000
	s_addc_u32 s9, s59, 0
	global_load_dwordx4 v[140:143], v6, s[8:9]
	s_add_u32 s8, s58, 0x150000
	s_addc_u32 s9, s59, 0
	global_load_dwordx4 v[144:147], v6, s[8:9]
	s_add_u32 s8, s58, 0x152000
	s_addc_u32 s9, s59, 0
	global_load_dwordx4 v[148:151], v6, s[8:9]
	s_add_u32 s8, s58, 0x168000
	s_addc_u32 s9, s59, 0
	global_load_dwordx4 v[152:155], v6, s[8:9]
	s_add_u32 s8, s58, 0x16a000
	s_addc_u32 s9, s59, 0
	global_load_dwordx4 v[156:159], v6, s[8:9]
	s_waitcnt vmcnt(30)
	v_pk_add_f32 v[12:13], v[12:13], v[24:25]
	v_pk_add_f32 v[14:15], v[14:15], v[26:27]
	v_pk_add_f32 v[16:17], v[16:17], v[28:29]
	v_pk_add_f32 v[18:19], v[18:19], v[30:31]
	s_waitcnt vmcnt(28)
	v_pk_add_f32 v[12:13], v[12:13], v[32:33]
	v_pk_add_f32 v[14:15], v[14:15], v[34:35]
	v_pk_add_f32 v[16:17], v[16:17], v[36:37]
	v_pk_add_f32 v[18:19], v[18:19], v[38:39]
	s_waitcnt vmcnt(26)
	v_pk_add_f32 v[12:13], v[12:13], v[40:41]
	v_pk_add_f32 v[14:15], v[14:15], v[42:43]
	v_pk_add_f32 v[16:17], v[16:17], v[44:45]
	v_pk_add_f32 v[18:19], v[18:19], v[46:47]
	s_waitcnt vmcnt(24)
	v_pk_add_f32 v[12:13], v[12:13], v[48:49]
	v_pk_add_f32 v[14:15], v[14:15], v[50:51]
	v_pk_add_f32 v[16:17], v[16:17], v[52:53]
	v_pk_add_f32 v[18:19], v[18:19], v[54:55]
	s_waitcnt vmcnt(22)
	v_pk_add_f32 v[12:13], v[12:13], v[56:57]
	v_pk_add_f32 v[14:15], v[14:15], v[58:59]
	v_pk_add_f32 v[16:17], v[16:17], v[60:61]
	v_pk_add_f32 v[18:19], v[18:19], v[62:63]
	s_waitcnt vmcnt(20)
	v_pk_add_f32 v[12:13], v[12:13], v[64:65]
	v_pk_add_f32 v[14:15], v[14:15], v[66:67]
	v_pk_add_f32 v[16:17], v[16:17], v[68:69]
	v_pk_add_f32 v[18:19], v[18:19], v[70:71]
	s_waitcnt vmcnt(18)
; __device__ __forceinline__ void p1_rows(const Params& P, LAS unsigned char* lds, int G) {
;     ...
;         float sh = P.b_ada[col], sc = P.b_ada[DM + col];
;         for (int ks = 0; ks < KS_ADA; ++ks) { sh += adap[(size_t)(ks * 2 + b) * NADA + col]; sc += adap[(size_t)(ks * 2 + b) * NADA + DM + col]; }
;         TA[idx] = P.g_pre_mix[col] * (1.0f + sc); TC[idx] = sh; }
	v_pk_add_f32 v[12:13], v[12:13], v[72:73]
	v_pk_add_f32 v[14:15], v[14:15], v[74:75]
	v_pk_add_f32 v[16:17], v[16:17], v[76:77]
	v_pk_add_f32 v[18:19], v[18:19], v[78:79]
	s_waitcnt vmcnt(16)
	v_pk_add_f32 v[12:13], v[12:13], v[80:81]
	v_pk_add_f32 v[14:15], v[14:15], v[82:83]
	v_pk_add_f32 v[16:17], v[16:17], v[84:85]
	v_pk_add_f32 v[18:19], v[18:19], v[86:87]
	s_waitcnt vmcnt(14)
	v_pk_add_f32 v[12:13], v[12:13], v[88:89]
	v_pk_add_f32 v[14:15], v[14:15], v[90:91]
	v_pk_add_f32 v[16:17], v[16:17], v[92:93]
	v_pk_add_f32 v[18:19], v[18:19], v[94:95]
	s_waitcnt vmcnt(12)
	v_pk_add_f32 v[12:13], v[12:13], v[96:97]
	v_pk_add_f32 v[14:15], v[14:15], v[98:99]
	v_pk_add_f32 v[16:17], v[16:17], v[100:101]
	v_pk_add_f32 v[18:19], v[18:19], v[102:103]
	s_waitcnt vmcnt(10)
	v_pk_add_f32 v[12:13], v[12:13], v[104:105]
	v_pk_add_f32 v[14:15], v[14:15], v[106:107]
	v_pk_add_f32 v[16:17], v[16:17], v[108:109]
	v_pk_add_f32 v[18:19], v[18:19], v[110:111]
	s_waitcnt vmcnt(8)
	v_pk_add_f32 v[12:13], v[12:13], v[112:113]
	v_pk_add_f32 v[14:15], v[14:15], v[114:115]
	v_pk_add_f32 v[16:17], v[16:17], v[116:117]
	v_pk_add_f32 v[18:19], v[18:19], v[118:119]
	s_waitcnt vmcnt(6)
	v_pk_add_f32 v[12:13], v[12:13], v[120:121]
	v_pk_add_f32 v[14:15], v[14:15], v[122:123]
	v_pk_add_f32 v[16:17], v[16:17], v[132:133]
	v_pk_add_f32 v[18:19], v[18:19], v[134:135]
	s_waitcnt vmcnt(4)
	v_pk_add_f32 v[12:13], v[12:13], v[136:137]
	v_pk_add_f32 v[14:15], v[14:15], v[138:139]
	v_pk_add_f32 v[16:17], v[16:17], v[140:141]
	v_pk_add_f32 v[18:19], v[18:19], v[142:143]
	s_waitcnt vmcnt(2)
	v_pk_add_f32 v[12:13], v[12:13], v[144:145]
	v_pk_add_f32 v[14:15], v[14:15], v[146:147]
	v_pk_add_f32 v[16:17], v[16:17], v[148:149]
	v_pk_add_f32 v[18:19], v[18:19], v[150:151]
	s_waitcnt vmcnt(0)
	v_pk_add_f32 v[12:13], v[12:13], v[152:153]
	v_pk_add_f32 v[14:15], v[14:15], v[154:155]
	v_pk_add_f32 v[16:17], v[16:17], v[156:157]
	v_pk_add_f32 v[18:19], v[18:19], v[158:159]
	v_add_f32_e32 v2, 1.0, v16
	v_add_f32_e32 v3, 1.0, v17
	v_add_f32_e32 v4, 1.0, v18
	v_add_f32_e32 v5, 1.0, v19
	v_mul_f32_e32 v2, v2, v20
	v_mul_f32_e32 v3, v3, v21
	v_mul_f32_e32 v4, v4, v22
	v_mul_f32_e32 v5, v5, v23
	v_mov_b32_e32 v7, v0
	ds_write_b128 v7, v[2:5]
	ds_write_b128 v7, v[12:15] offset:16384
	v_add_u32_e32 v6, 0xc000, v0
	s_add_u32 s8, s68, 0x2000
	s_addc_u32 s9, s69, 0
	global_load_dwordx4 v[12:15], v0, s[68:69]
	global_load_dwordx4 v[16:19], v0, s[8:9]
	global_load_dwordx4 v[20:23], v0, s[70:71]
	s_add_u32 s8, s58, 0x0
	s_addc_u32 s9, s59, 0
	global_load_dwordx4 v[24:27], v6, s[8:9]
	s_add_u32 s8, s58, 0x2000
	s_addc_u32 s9, s59, 0
	global_load_dwordx4 v[28:31], v6, s[8:9]
	s_add_u32 s8, s58, 0x18000
	s_addc_u32 s9, s59, 0
	global_load_dwordx4 v[32:35], v6, s[8:9]
	s_add_u32 s8, s58, 0x1a000
	s_addc_u32 s9, s59, 0
	global_load_dwordx4 v[36:39], v6, s[8:9]
	s_add_u32 s8, s58, 0x30000
	s_addc_u32 s9, s59, 0
	global_load_dwordx4 v[40:43], v6, s[8:9]
	s_add_u32 s8, s58, 0x32000
	s_addc_u32 s9, s59, 0
	global_load_dwordx4 v[44:47], v6, s[8:9]
	s_add_u32 s8, s58, 0x48000
	s_addc_u32 s9, s59, 0
	global_load_dwordx4 v[48:51], v6, s[8:9]
	s_add_u32 s8, s58, 0x4a000
	s_addc_u32 s9, s59, 0
	global_load_dwordx4 v[52:55], v6, s[8:9]
	s_add_u32 s8, s58, 0x60000
	s_addc_u32 s9, s59, 0
	global_load_dwordx4 v[56:59], v6, s[8:9]
	s_add_u32 s8, s58, 0x62000
	s_addc_u32 s9, s59, 0
	global_load_dwordx4 v[60:63], v6, s[8:9]
	s_add_u32 s8, s58, 0x78000
	s_addc_u32 s9, s59, 0
	global_load_dwordx4 v[64:67], v6, s[8:9]
	s_add_u32 s8, s58, 0x7a000
	s_addc_u32 s9, s59, 0
	global_load_dwordx4 v[68:71], v6, s[8:9]
	s_add_u32 s8, s58, 0x90000
	s_addc_u32 s9, s59, 0
	global_load_dwordx4 v[72:75], v6, s[8:9]
	s_add_u32 s8, s58, 0x92000
	s_addc_u32 s9, s59, 0
	global_load_dwordx4 v[76:79], v6, s[8:9]
	s_add_u32 s8, s58, 0xa8000
	s_addc_u32 s9, s59, 0
	global_load_dwordx4 v[80:83], v6, s[8:9]
	s_add_u32 s8, s58, 0xaa000
	s_addc_u32 s9, s59, 0
	global_load_dwordx4 v[84:87], v6, s[8:9]
	s_add_u32 s8, s58, 0xc0000
	s_addc_u32 s9, s59, 0
	global_load_dwordx4 v[88:91], v6, s[8:9]
	s_add_u32 s8, s58, 0xc2000
	s_addc_u32 s9, s59, 0
	global_load_dwordx4 v[92:95], v6, s[8:9]
	s_add_u32 s8, s58, 0xd8000
	s_addc_u32 s9, s59, 0
	global_load_dwordx4 v[96:99], v6, s[8:9]
	s_add_u32 s8, s58, 0xda000
	s_addc_u32 s9, s59, 0
	global_load_dwordx4 v[100:103], v6, s[8:9]
	s_add_u32 s8, s58, 0xf0000
	s_addc_u32 s9, s59, 0
	global_load_dwordx4 v[104:107], v6, s[8:9]
	s_add_u32 s8, s58, 0xf2000
	s_addc_u32 s9, s59, 0
	global_load_dwordx4 v[108:111], v6, s[8:9]
	s_add_u32 s8, s58, 0x108000
	s_addc_u32 s9, s59, 0
	global_load_dwordx4 v[112:115], v6, s[8:9]
	s_add_u32 s8, s58, 0x10a000
	s_addc_u32 s9, s59, 0
	global_load_dwordx4 v[116:119], v6, s[8:9]
	s_add_u32 s8, s58, 0x120000
	s_addc_u32 s9, s59, 0
	global_load_dwordx4 v[120:123], v6, s[8:9]
	s_add_u32 s8, s58, 0x122000
	s_addc_u32 s9, s59, 0
	global_load_dwordx4 v[132:135], v6, s[8:9]
	s_add_u32 s8, s58, 0x138000
	s_addc_u32 s9, s59, 0
	global_load_dwordx4 v[136:139], v6, s[8:9]
	s_add_u32 s8, s58, 0x13a000
	s_addc_u32 s9, s59, 0
	global_load_dwordx4 v[140:143], v6, s[8:9]
	s_add_u32 s8, s58, 0x150000
	s_addc_u32 s9, s59, 0
	global_load_dwordx4 v[144:147], v6, s[8:9]
	s_add_u32 s8, s58, 0x152000
	s_addc_u32 s9, s59, 0
	global_load_dwordx4 v[148:151], v6, s[8:9]
	s_add_u32 s8, s58, 0x168000
	s_addc_u32 s9, s59, 0
	global_load_dwordx4 v[152:155], v6, s[8:9]
	s_add_u32 s8, s58, 0x16a000
	s_addc_u32 s9, s59, 0
	global_load_dwordx4 v[156:159], v6, s[8:9]
	s_waitcnt vmcnt(30)
; __device__ __forceinline__ void p1_rows(const Params& P, LAS unsigned char* lds, int G) {
;     ...
;         for (int ks = 0; ks < KS_ADA; ++ks) { sh += adap[(size_t)(ks * 2 + b) * NADA + col]; sc += adap[(size_t)(ks * 2 + b) * NADA + DM + col]; }
;         TA[idx] = P.g_pre_mix[col] * (1.0f + sc); TC[idx] = sh; }
	v_pk_add_f32 v[12:13], v[12:13], v[24:25]
	v_pk_add_f32 v[14:15], v[14:15], v[26:27]
	v_pk_add_f32 v[16:17], v[16:17], v[28:29]
	v_pk_add_f32 v[18:19], v[18:19], v[30:31]
	s_waitcnt vmcnt(28)
	v_pk_add_f32 v[12:13], v[12:13], v[32:33]
	v_pk_add_f32 v[14:15], v[14:15], v[34:35]
	v_pk_add_f32 v[16:17], v[16:17], v[36:37]
	v_pk_add_f32 v[18:19], v[18:19], v[38:39]
	s_waitcnt vmcnt(26)
	v_pk_add_f32 v[12:13], v[12:13], v[40:41]
	v_pk_add_f32 v[14:15], v[14:15], v[42:43]
	v_pk_add_f32 v[16:17], v[16:17], v[44:45]
	v_pk_add_f32 v[18:19], v[18:19], v[46:47]
	s_waitcnt vmcnt(24)
	v_pk_add_f32 v[12:13], v[12:13], v[48:49]
	v_pk_add_f32 v[14:15], v[14:15], v[50:51]
	v_pk_add_f32 v[16:17], v[16:17], v[52:53]
	v_pk_add_f32 v[18:19], v[18:19], v[54:55]
	s_waitcnt vmcnt(22)
	v_pk_add_f32 v[12:13], v[12:13], v[56:57]
	v_pk_add_f32 v[14:15], v[14:15], v[58:59]
	v_pk_add_f32 v[16:17], v[16:17], v[60:61]
	v_pk_add_f32 v[18:19], v[18:19], v[62:63]
	s_waitcnt vmcnt(20)
	v_pk_add_f32 v[12:13], v[12:13], v[64:65]
	v_pk_add_f32 v[14:15], v[14:15], v[66:67]
	v_pk_add_f32 v[16:17], v[16:17], v[68:69]
	v_pk_add_f32 v[18:19], v[18:19], v[70:71]
	s_waitcnt vmcnt(18)
	v_pk_add_f32 v[12:13], v[12:13], v[72:73]
	v_pk_add_f32 v[14:15], v[14:15], v[74:75]
	v_pk_add_f32 v[16:17], v[16:17], v[76:77]
	v_pk_add_f32 v[18:19], v[18:19], v[78:79]
	s_waitcnt vmcnt(16)
	v_pk_add_f32 v[12:13], v[12:13], v[80:81]
	v_pk_add_f32 v[14:15], v[14:15], v[82:83]
	v_pk_add_f32 v[16:17], v[16:17], v[84:85]
	v_pk_add_f32 v[18:19], v[18:19], v[86:87]
	s_waitcnt vmcnt(14)
	v_pk_add_f32 v[12:13], v[12:13], v[88:89]
	v_pk_add_f32 v[14:15], v[14:15], v[90:91]
	v_pk_add_f32 v[16:17], v[16:17], v[92:93]
	v_pk_add_f32 v[18:19], v[18:19], v[94:95]
	s_waitcnt vmcnt(12)
	v_pk_add_f32 v[12:13], v[12:13], v[96:97]
	v_pk_add_f32 v[14:15], v[14:15], v[98:99]
	v_pk_add_f32 v[16:17], v[16:17], v[100:101]
	v_pk_add_f32 v[18:19], v[18:19], v[102:103]
	s_waitcnt vmcnt(10)
	v_pk_add_f32 v[12:13], v[12:13], v[104:105]
	v_pk_add_f32 v[14:15], v[14:15], v[106:107]
	v_pk_add_f32 v[16:17], v[16:17], v[108:109]
	v_pk_add_f32 v[18:19], v[18:19], v[110:111]
	s_waitcnt vmcnt(8)
	v_pk_add_f32 v[12:13], v[12:13], v[112:113]
	v_pk_add_f32 v[14:15], v[14:15], v[114:115]
	v_pk_add_f32 v[16:17], v[16:17], v[116:117]
	v_pk_add_f32 v[18:19], v[18:19], v[118:119]
	s_waitcnt vmcnt(6)
	v_pk_add_f32 v[12:13], v[12:13], v[120:121]
	v_pk_add_f32 v[14:15], v[14:15], v[122:123]
	v_pk_add_f32 v[16:17], v[16:17], v[132:133]
	v_pk_add_f32 v[18:19], v[18:19], v[134:135]
	s_waitcnt vmcnt(4)
	v_pk_add_f32 v[12:13], v[12:13], v[136:137]
	v_pk_add_f32 v[14:15], v[14:15], v[138:139]
	v_pk_add_f32 v[16:17], v[16:17], v[140:141]
	v_pk_add_f32 v[18:19], v[18:19], v[142:143]
	s_waitcnt vmcnt(2)
	v_pk_add_f32 v[12:13], v[12:13], v[144:145]
	v_pk_add_f32 v[14:15], v[14:15], v[146:147]
	v_pk_add_f32 v[16:17], v[16:17], v[148:149]
	v_pk_add_f32 v[18:19], v[18:19], v[150:151]
	s_waitcnt vmcnt(0)
	v_pk_add_f32 v[12:13], v[12:13], v[152:153]
	v_pk_add_f32 v[14:15], v[14:15], v[154:155]
	v_pk_add_f32 v[16:17], v[16:17], v[156:157]
	v_pk_add_f32 v[18:19], v[18:19], v[158:159]
	v_add_f32_e32 v2, 1.0, v16
	v_add_f32_e32 v3, 1.0, v17
	v_add_f32_e32 v4, 1.0, v18
	v_add_f32_e32 v5, 1.0, v19
	v_mul_f32_e32 v2, v2, v20
	v_mul_f32_e32 v3, v3, v21
	v_mul_f32_e32 v4, v4, v22
	v_mul_f32_e32 v5, v5, v23
	v_add_u32_e32 v7, 0x2000, v0
	ds_write_b128 v7, v[2:5]
	ds_write_b128 v7, v[12:15] offset:16384

; __device__ __forceinline__ void p1_rows(const Params& P, LAS unsigned char* lds, int G) {
;     ...
;     __syncthreads();
;     bf16_t* XN = (bf16_t*)(P.ws + WS_XN);
;     for (int m = blockIdx.x * 8 + wave; m < M; m += G * 8) {
;         const int b = m >> 13; const f32x4* xr = (const f32x4*)(P.x + (size_t)m * DM) + lane;
;         f32x4 v[8]; float ss = 0.f;
; #pragma unroll
;         for (int j = 0; j < 8; ++j) { v[j] = __builtin_nontemporal_load(xr + 64 * j); ss += (v[j][0] * v[j][0] + v[j][1] * v[j][1]) + (v[j][2] * v[j][2] + v[j][3] * v[j][3]); }
;         const float rstd = rsqrtf(wave_sum(ss) * (1.0f / DM) + RMS_EPS);
;         u32x2* o = (u32x2*)(XN + (size_t)m * DM) + lane;
.LBB0_166:
	s_or_b64 exec, exec, s[4:5]
	v_ashrrev_i32_e32 v0, 6, v8
	s_lshl_b32 s4, s2, 3
	v_writelane_b32 v241, s4, 15
	s_and_b32 s6, s2, 7
	s_lshl_b32 s6, s6, 11
	s_lshr_b32 s4, s2, 3
	s_lshl_b32 s4, s4, 3
	s_add_i32 s4, s4, s6
	s_lshl_b32 s6, s2, 3
	s_cmpk_eq_u32 s92, 0x100
	s_cselect_b32 s4, s4, s6
	v_add_u32_e32 v32, s4, v0
	s_movk_i32 s4, 0x4000
	v_cmp_gt_i32_e32 vcc, s4, v32
	v_mbcnt_lo_u32_b32 v208, -1, 0
	s_waitcnt lgkmcnt(0)
	s_barrier
	s_and_saveexec_b64 s[4:5], vcc
	s_cbranch_execz .LBB0_169
	v_mbcnt_hi_u32_b32 v0, -1, v208
	v_and_b32_e32 v1, 64, v0
	v_add_u32_e32 v1, 64, v1
	v_xor_b32_e32 v3, 1, v0
	v_cmp_lt_i32_e32 vcc, v3, v1
	v_and_b32_e32 v2, 63, v8
	v_ashrrev_i32_e32 v33, 31, v32
	v_cndmask_b32_e32 v3, v0, v3, vcc
	v_lshlrev_b32_e32 v38, 2, v3
	v_xor_b32_e32 v3, 2, v0
	v_cmp_lt_i32_e32 vcc, v3, v1
	s_mov_b64 s[6:7], 0x1000
	s_cmpk_eq_u32 s92, 0x100
	s_cselect_b32 s42, 0x100, s42
	s_ashr_i32 s43, s42, 31
	v_cndmask_b32_e32 v3, v0, v3, vcc
	v_lshlrev_b32_e32 v39, 2, v3
	v_xor_b32_e32 v3, 4, v0
	v_cmp_lt_i32_e32 vcc, v3, v1
	s_mov_b64 s[8:9], 0x6800000
	s_mov_b64 s[10:11], 0
	v_cndmask_b32_e32 v3, v0, v3, vcc
	v_lshlrev_b32_e32 v40, 2, v3
	v_xor_b32_e32 v3, 8, v0
	v_cmp_lt_i32_e32 vcc, v3, v1
	s_mov_b32 s12, 0x800000
	s_and_b32 s13, s2, 7
	s_lshl_b32 s13, s13, 11
	s_addk_i32 s13, 0x7ff
	s_cmpk_eq_u32 s92, 0x100
	s_cselect_b32 s13, s13, 0x3fff
	v_cndmask_b32_e32 v3, v0, v3, vcc
	v_lshlrev_b32_e32 v41, 2, v3
	v_xor_b32_e32 v3, 16, v0
	v_cmp_lt_i32_e32 vcc, v3, v1
	s_nop 1
	v_cndmask_b32_e32 v3, v0, v3, vcc
	v_lshlrev_b32_e32 v42, 2, v3
	v_xor_b32_e32 v3, 32, v0
	v_cmp_lt_i32_e32 vcc, v3, v1
	s_nop 1
	v_cndmask_b32_e32 v0, v0, v3, vcc
	v_lshlrev_b32_e32 v43, 2, v0
	v_lshlrev_b32_e32 v3, 4, v2
	v_lshlrev_b64 v[0:1], 13, v[32:33]
	v_or_b32_e32 v0, v0, v3
	v_lshl_add_u64 v[0:1], s[60:61], 0, v[0:1]
	v_lshl_add_u64 v[34:35], v[0:1], 0, s[6:7]
	v_lshlrev_b64 v[0:1], 12, v[32:33]
	v_lshl_or_b32 v0, v2, 3, v0
	v_lshl_add_u64 v[0:1], s[58:59], 0, v[0:1]
	v_add_u32_e32 v44, 0, v3
	s_lshl_b64 s[6:7], s[42:43], 13
	v_lshl_add_u64 v[36:37], v[0:1], 0, s[8:9]
	s_lshl_b64 s[8:9], s[42:43], 12
	v_mov_b32_e32 v33, 0x358637bd
	s_waitcnt vmcnt(0)
	v_mov_b32_e32 v4, v170
	v_mov_b32_e32 v5, v171
	v_mov_b32_e32 v6, v172
	v_mov_b32_e32 v7, v173
	v_mov_b32_e32 v0, v202
	v_mov_b32_e32 v1, v203
	v_mov_b32_e32 v2, v204
	v_mov_b32_e32 v3, v205
	v_mov_b32_e32 v8, v210
	v_mov_b32_e32 v9, v211
	v_mov_b32_e32 v10, v212
	v_mov_b32_e32 v11, v213
	v_mov_b32_e32 v12, v222
	v_mov_b32_e32 v13, v223
	v_mov_b32_e32 v14, v224
	v_mov_b32_e32 v15, v225
	v_mov_b32_e32 v16, v218
	v_mov_b32_e32 v17, v219
	v_mov_b32_e32 v18, v220
	v_mov_b32_e32 v19, v221
	v_mov_b32_e32 v20, v214
	v_mov_b32_e32 v21, v215
	v_mov_b32_e32 v22, v216
	v_mov_b32_e32 v23, v217
	v_mov_b32_e32 v24, v250
	v_mov_b32_e32 v25, v251
	v_mov_b32_e32 v26, v252
	v_mov_b32_e32 v27, v253
	v_mov_b32_e32 v28, v246
	v_mov_b32_e32 v29, v247
	v_mov_b32_e32 v30, v248
	v_mov_b32_e32 v31, v249
	s_branch .Lp1_first

; #define LAS __attribute__((address_space(3)))
; __device__ __forceinline__ void p1_rows(const Params& P, LAS unsigned char* lds, int G) {
;     ...
;         for (int j = 0; j < 8; ++j) { v[j] = __builtin_nontemporal_load(xr + 64 * j); ss += (v[j][0] * v[j][0] + v[j][1] * v[j][1]) + (v[j][2] * v[j][2] + v[j][3] * v[j][3]); }
;         const float rstd = rsqrtf(wave_sum(ss) * (1.0f / DM) + RMS_EPS);
;         u32x2* o = (u32x2*)(XN + (size_t)m * DM) + lane;
; #pragma unroll
;         for (int j = 0; j < 8; ++j) { const f32x4 a = *(const LAS f32x4*)(TA + b * DM + 256 * j + 4 * lane), c = *(const LAS f32x4*)(TC + b * DM + 256 * j + 4 * lane);
.Lp1_first:
	v_and_b32_e32 v45, 0xffffe000, v32
	v_add_u32_e32 v45, v44, v45
	ds_read_b128 v[46:49], v45
	ds_read_b128 v[50:53], v45 offset:1024
	ds_read_b128 v[54:57], v45 offset:16384
	ds_read_b128 v[58:61], v45 offset:17408
	ds_read_b128 v[62:65], v45 offset:2048
	ds_read_b128 v[66:69], v45 offset:3072
	ds_read_b128 v[70:73], v45 offset:18432
	ds_read_b128 v[74:77], v45 offset:19456
	ds_read_b128 v[78:81], v45 offset:4096
	ds_read_b128 v[82:85], v45 offset:5120
	ds_read_b128 v[86:89], v45 offset:20480
	ds_read_b128 v[90:93], v45 offset:21504
	ds_read_b128 v[94:97], v45 offset:6144
	ds_read_b128 v[98:101], v45 offset:7168
	ds_read_b128 v[102:105], v45 offset:22528
	ds_read_b128 v[106:109], v45 offset:23552
	v_add_u32_e32 v32, s42, v32
	v_cmp_lt_i32_e32 vcc, s13, v32
	s_or_b64 s[10:11], vcc, s[10:11]
	v_lshl_add_u64 v[34:35], v[34:35], 0, s[6:7]
	s_waitcnt vmcnt(7)
	v_mov_b32_e32 v112, v5
	s_waitcnt vmcnt(6)
	v_mov_b32_e32 v113, v1
	s_waitcnt vmcnt(5)
	v_pk_mul_f32 v[114:115], v[10:11], v[10:11]
	v_pk_mul_f32 v[116:117], v[8:9], v[8:9]
	s_waitcnt vmcnt(4)
	v_pk_mul_f32 v[118:119], v[14:15], v[14:15]
	v_pk_mul_f32 v[120:121], v[12:13], v[12:13]
	v_mov_b32_e32 v124, v7
	v_mov_b32_e32 v125, v3
	v_mov_b32_e32 v110, v4
	v_mov_b32_e32 v111, v0
	v_mov_b32_e32 v122, v6
	v_mov_b32_e32 v123, v2
	v_pk_mov_b32 v[134:135], v[116:117], v[114:115] op_sel:[1,0]
	v_mov_b32_e32 v117, v115
	v_pk_mov_b32 v[114:115], v[120:121], v[118:119] op_sel:[1,0]
	v_mov_b32_e32 v121, v119
	v_pk_mul_f32 v[112:113], v[112:113], v[112:113]
	v_pk_mul_f32 v[118:119], v[124:125], v[124:125]
	v_pk_fma_f32 v[110:111], v[110:111], v[110:111], v[112:113]
	v_pk_fma_f32 v[112:113], v[122:123], v[122:123], v[118:119]
	s_waitcnt vmcnt(2)
	v_mul_f32_e32 v126, v21, v21
	v_mul_f32_e32 v128, v23, v23
	v_pk_add_f32 v[116:117], v[134:135], v[116:117]
	v_pk_add_f32 v[110:111], v[110:111], v[112:113]
	v_mul_f32_e32 v45, v16, v16
	v_mul_f32_e32 v133, v18, v18
	v_mul_f32_e32 v136, v19, v19
	v_mul_f32_e32 v139, v17, v17
	v_pk_fma_f32 v[124:125], v[20:21], v[20:21], v[126:127] op_sel_hi:[1,1,0]
	v_pk_fma_f32 v[126:127], v[22:23], v[22:23], v[128:129] op_sel_hi:[1,1,0]
	v_pk_add_f32 v[116:117], v[116:117], v[116:117] op_sel:[0,1] op_sel_hi:[1,0]
	v_pk_add_f32 v[110:111], v[110:111], v[110:111] op_sel:[0,1] op_sel_hi:[1,0]
	v_mov_b32_e32 v125, v133
	v_mov_b32_e32 v127, v136
	v_mov_b32_e32 v117, v139
	v_mov_b32_e32 v111, v45
	v_pk_add_f32 v[112:113], v[124:125], v[126:127]
	v_pk_add_f32 v[110:111], v[110:111], v[116:117]
	s_waitcnt vmcnt(0)
	v_mul_f32_e32 v130, v29, v29
	v_mul_f32_e32 v132, v31, v31
	v_pk_add_f32 v[114:115], v[114:115], v[120:121]
	v_pk_add_f32 v[110:111], v[110:111], v[112:113]
	v_mul_f32_e32 v137, v26, v26
	v_mul_f32_e32 v138, v27, v27
	v_mul_f32_e32 v140, v24, v24
	v_mul_f32_e32 v141, v25, v25
	v_pk_fma_f32 v[128:129], v[28:29], v[28:29], v[130:131] op_sel_hi:[1,1,0]
	v_pk_fma_f32 v[130:131], v[30:31], v[30:31], v[132:133] op_sel_hi:[1,1,0]
	v_pk_add_f32 v[114:115], v[114:115], v[114:115] op_sel:[0,1] op_sel_hi:[1,0]
	v_pk_add_f32 v[110:111], v[110:111], v[110:111] op_sel:[0,1] op_sel_hi:[1,0]
	v_mov_b32_e32 v129, v137
	v_mov_b32_e32 v131, v138
	v_mov_b32_e32 v115, v141
	v_mov_b32_e32 v111, v140
	v_pk_add_f32 v[118:119], v[128:129], v[130:131]
	v_pk_add_f32 v[110:111], v[110:111], v[114:115]
	s_nop 0
	v_pk_add_f32 v[110:111], v[110:111], v[118:119]
	s_nop 0
	v_add_f32_e32 v45, v110, v111
	s_nop 1
	v_add_f32_dpp v45, v45, v45 quad_perm:[1,0,3,2] row_mask:0xf bank_mask:0xf
	s_nop 1
	v_add_f32_dpp v45, v45, v45 quad_perm:[2,3,0,1] row_mask:0xf bank_mask:0xf
	s_nop 1
	v_add_f32_dpp v45, v45, v45 row_half_mirror row_mask:0xf bank_mask:0xf
	s_nop 1
	v_add_f32_dpp v45, v45, v45 row_mirror row_mask:0xf bank_mask:0xf
	v_mov_b32_e32 v110, v45
	s_nop 1
	v_permlane16_swap_b32_e32 v110, v45
	v_add_f32_e32 v45, v45, v110
	v_mov_b32_e32 v110, v45
	s_nop 1
	v_permlane32_swap_b32_e32 v110, v45
	v_add_f32_e32 v45, v45, v110
	s_waitcnt lgkmcnt(0)
; #define LAS __attribute__((address_space(3)))
; __device__ __forceinline__ unsigned pk2(float lo, float hi) { return pg8::cvtpk(lo, hi); }
; __device__ __forceinline__ void p1_rows(const Params& P, LAS unsigned char* lds, int G) {
;     ...
;         const float rstd = rsqrtf(wave_sum(ss) * (1.0f / DM) + RMS_EPS);
;         u32x2* o = (u32x2*)(XN + (size_t)m * DM) + lane;
; #pragma unroll
;         for (int j = 0; j < 8; ++j) { const f32x4 a = *(const LAS f32x4*)(TA + b * DM + 256 * j + 4 * lane), c = *(const LAS f32x4*)(TC + b * DM + 256 * j + 4 * lane);
;             const f32x4 h = v[j] * rstd * a + c; u32x2 w; w.x = pk2(h[0], h[1]); w.y = pk2(h[2], h[3]); o[64 * j] = w; }
;     }
	v_fmamk_f32 v45, v45, 0x3a000000, v33
	v_mul_f32_e32 v110, 0x4b800000, v45
	v_cmp_gt_f32_e32 vcc, s12, v45
	s_nop 1
	v_cndmask_b32_e32 v45, v45, v110, vcc
	v_rsq_f32_e32 v45, v45
	s_nop 0
	v_mul_f32_e32 v110, 0x45800000, v45
	v_cndmask_b32_e32 v110, v45, v110, vcc
	v_pk_mul_f32 v[4:5], v[4:5], v[110:111] op_sel_hi:[1,0]
	v_pk_mul_f32 v[6:7], v[6:7], v[110:111] op_sel_hi:[1,0]
	v_pk_mul_f32 v[0:1], v[0:1], v[110:111] op_sel_hi:[1,0]
	v_pk_mul_f32 v[2:3], v[2:3], v[110:111] op_sel_hi:[1,0]
	v_pk_mul_f32 v[8:9], v[8:9], v[110:111] op_sel_hi:[1,0]
	v_pk_mul_f32 v[10:11], v[10:11], v[110:111] op_sel_hi:[1,0]
	v_pk_mul_f32 v[20:21], v[20:21], v[110:111] op_sel_hi:[1,0]
	v_pk_mul_f32 v[22:23], v[22:23], v[110:111] op_sel_hi:[1,0]
	v_pk_mul_f32 v[16:17], v[16:17], v[110:111] op_sel_hi:[1,0]
	v_pk_mul_f32 v[18:19], v[18:19], v[110:111] op_sel_hi:[1,0]
	v_pk_mul_f32 v[12:13], v[12:13], v[110:111] op_sel_hi:[1,0]
	v_pk_mul_f32 v[14:15], v[14:15], v[110:111] op_sel_hi:[1,0]
	v_pk_mul_f32 v[28:29], v[28:29], v[110:111] op_sel_hi:[1,0]
	v_pk_mul_f32 v[30:31], v[30:31], v[110:111] op_sel_hi:[1,0]
	v_pk_mul_f32 v[24:25], v[24:25], v[110:111] op_sel_hi:[1,0]
	v_pk_mul_f32 v[26:27], v[26:27], v[110:111] op_sel_hi:[1,0]
	v_pk_fma_f32 v[6:7], v[48:49], v[6:7], v[56:57]
	v_pk_fma_f32 v[4:5], v[46:47], v[4:5], v[54:55]
	v_pk_fma_f32 v[2:3], v[52:53], v[2:3], v[60:61]
	v_pk_fma_f32 v[0:1], v[50:51], v[0:1], v[58:59]
	v_pk_fma_f32 v[10:11], v[64:65], v[10:11], v[72:73]
	v_pk_fma_f32 v[8:9], v[62:63], v[8:9], v[70:71]
	v_pk_fma_f32 v[22:23], v[68:69], v[22:23], v[76:77]
	v_pk_fma_f32 v[20:21], v[66:67], v[20:21], v[74:75]
	v_pk_fma_f32 v[18:19], v[80:81], v[18:19], v[88:89]
	v_pk_fma_f32 v[16:17], v[78:79], v[16:17], v[86:87]
	v_pk_fma_f32 v[14:15], v[14:15], v[84:85], v[92:93]
	v_pk_fma_f32 v[12:13], v[12:13], v[82:83], v[90:91]
	v_pk_fma_f32 v[30:31], v[30:31], v[96:97], v[104:105]
	v_pk_fma_f32 v[28:29], v[28:29], v[94:95], v[102:103]
	v_pk_fma_f32 v[26:27], v[26:27], v[100:101], v[108:109]
	v_pk_fma_f32 v[24:25], v[24:25], v[98:99], v[106:107]
	v_cvt_pk_bf16_f32 v4, v4, v5
	v_cvt_pk_bf16_f32 v5, v6, v7
	v_cvt_pk_bf16_f32 v0, v0, v1
	v_cvt_pk_bf16_f32 v1, v2, v3
	v_cvt_pk_bf16_f32 v2, v8, v9
	v_cvt_pk_bf16_f32 v3, v10, v11
	v_cvt_pk_bf16_f32 v6, v20, v21
	v_cvt_pk_bf16_f32 v7, v22, v23
	v_cvt_pk_bf16_f32 v8, v16, v17
	v_cvt_pk_bf16_f32 v9, v18, v19
	v_cvt_pk_bf16_f32 v10, v12, v13
	v_cvt_pk_bf16_f32 v11, v14, v15
	v_cvt_pk_bf16_f32 v12, v28, v29
	v_cvt_pk_bf16_f32 v13, v30, v31
	v_cvt_pk_bf16_f32 v14, v24, v25
	v_cvt_pk_bf16_f32 v15, v26, v27
	global_store_dwordx2 v[36:37], v[4:5], off
	global_store_dwordx2 v[36:37], v[0:1], off offset:512
	global_store_dwordx2 v[36:37], v[2:3], off offset:1024
	global_store_dwordx2 v[36:37], v[6:7], off offset:1536
	global_store_dwordx2 v[36:37], v[8:9], off offset:2048
	global_store_dwordx2 v[36:37], v[10:11], off offset:2560
	global_store_dwordx2 v[36:37], v[12:13], off offset:3072
	global_store_dwordx2 v[36:37], v[14:15], off offset:3584
	v_lshl_add_u64 v[36:37], v[36:37], 0, s[8:9]
	s_andn2_b64 exec, exec, s[10:11]
	s_cbranch_execnz .LBB0_168
